# XCD-local barriers for the three GEMM-to-GEMM seams (leader skips the cross-XCD hop) guarded by a run-time check that every blockIdx%8 group sits on one XCC
# speedup vs baseline: 1.0038x; 1.0038x over previous
_Z6mk_fwd4Args:
	s_mov_b32 s74, s2
	s_load_dword s2, s[0:1], 0x98
	s_load_dwordx4 s[76:79], s[0:1], 0x80
	s_load_dwordx2 s[52:53], s[0:1], 0x90
	s_add_u32 s4, s0, 0x90
	v_and_b32_e32 v171, 0x3ff, v0
	s_addc_u32 s5, s1, 0
	v_readfirstlane_b32 s48, v171
	v_cmp_gt_u32_e32 vcc, 2, v171
	s_waitcnt lgkmcnt(0)
	v_writelane_b32 v246, s2, 0
	s_and_saveexec_b64 s[2:3], vcc
	v_lshl_add_u32 v1, v171, 2, 0
	v_add_u32_e32 v1, 0x20000, v1
	v_mov_b32_e32 v2, 0
	ds_write_b32 v1, v2
	s_or_b64 exec, exec, s[2:3]
	s_add_u32 s2, s76, 0x280000
	s_addc_u32 s3, s77, 0
	v_writelane_b32 v246, s2, 1
	s_sub_i32 s10, s79, s78
	s_cmp_lt_i32 s10, 2
	v_writelane_b32 v246, s3, 2
	s_mov_b32 s2, 0
	v_cmp_eq_u32_e32 vcc, 0, v171
	s_waitcnt lgkmcnt(0)
	s_barrier
	v_writelane_b32 v246, s2, 3
	s_cbranch_scc1 .LBB0_7
	s_getreg_b32 s2, hwreg(HW_REG_XCC_ID, 0, 4)
	s_and_b32 s2, s2, 15
	v_writelane_b32 v246, s2, 3
	s_and_saveexec_b64 s[2:3], vcc
	s_cbranch_execz .LBB0_6
	s_mov_b64 s[6:7], exec
	v_mbcnt_lo_u32_b32 v1, s6, 0
	v_mbcnt_hi_u32_b32 v1, s7, v1
	v_cmp_eq_u32_e32 vcc, 0, v1
	s_and_b64 s[8:9], exec, vcc
	s_mov_b64 exec, s[8:9]
	s_cbranch_execz .LBB0_6
	v_readlane_b32 s8, v246, 3
	s_bcnt1_i32_b64 s6, s[6:7]
	s_lshl_b32 s8, s8, 8
	v_mov_b32_e32 v2, s6
	v_readlane_b32 s6, v246, 1
	v_mov_b32_e32 v1, s8
	v_readlane_b32 s7, v246, 2
	s_nop 4
	global_atomic_add v1, v2, s[6:7] offset:1024
	v_readlane_b32 s8, v246, 3
	s_and_b32 s9, s74, 7
	s_lshl_b32 s9, s9, 2
	s_addk_i32 s9, 0x3700
	v_mov_b32_e32 v1, s9
	s_add_i32 s9, s8, 1
	v_mov_b32_e32 v2, s9
	s_sub_i32 s8, 16, s8
	v_mov_b32_e32 v3, s8
	global_atomic_umax v1, v2, s[6:7]
	global_atomic_umax v1, v3, s[6:7] offset:256

.LBB0_724:
	s_andn2_saveexec_b64 s[6:7], s[6:7]
	s_cbranch_execz .LBB0_742
	s_mov_b64 s[6:7], exec
	buffer_wbl2 sc1
	v_readlane_b32 s98, v246, 1
	v_readlane_b32 s99, v246, 2
	v_mov_b32_e32 v20, 0x3700
	s_nop 4
	global_load_dwordx4 v[24:27], v20, s[98:99] sc1
	global_load_dwordx4 v[28:31], v20, s[98:99] offset:16 sc1
	global_load_dwordx4 v[32:35], v20, s[98:99] offset:256 sc1
	global_load_dwordx4 v[40:43], v20, s[98:99] offset:272 sc1
	buffer_inv sc1
	s_waitcnt lgkmcnt(0)
	s_waitcnt vmcnt(0)
	v_add_u32_e32 v24, v24, v32
	v_xor_b32_e32 v24, 17, v24
	v_add_u32_e32 v25, v25, v33
	v_xor_b32_e32 v25, 17, v25
	v_add_u32_e32 v26, v26, v34
	v_xor_b32_e32 v26, 17, v26
	v_add_u32_e32 v27, v27, v35
	v_xor_b32_e32 v27, 17, v27
	v_add_u32_e32 v28, v28, v40
	v_xor_b32_e32 v28, 17, v28
	v_add_u32_e32 v29, v29, v41
	v_xor_b32_e32 v29, 17, v29
	v_add_u32_e32 v30, v30, v42
	v_xor_b32_e32 v30, 17, v30
	v_add_u32_e32 v31, v31, v43
	v_xor_b32_e32 v31, 17, v31
	v_or3_b32 v24, v24, v25, v26
	v_or3_b32 v27, v27, v28, v29
	v_or3_b32 v24, v24, v30, v31
	v_or_b32_e32 v24, v24, v27
	v_cmp_eq_u32_e32 vcc, 0, v24
	s_cbranch_vccnz .LBB0_741
	v_mbcnt_lo_u32_b32 v1, s6, 0
	v_mbcnt_hi_u32_b32 v1, s7, v1
	v_cmp_eq_u32_e32 vcc, 0, v1
	s_and_saveexec_b64 s[8:9], vcc
	s_cbranch_execz .LBB0_727
	s_bcnt1_i32_b64 s6, s[6:7]
	v_mov_b32_e32 v2, 0x283000
	v_mov_b32_e32 v3, s6
	global_atomic_add v2, v2, v3, s[76:77] offset:1024 sc0

.LBB0_859:
	s_andn2_saveexec_b64 s[8:9], s[8:9]
	s_cbranch_execz .LBB0_877
	s_mov_b64 s[8:9], exec
	buffer_wbl2 sc1
	v_readlane_b32 s98, v246, 1
	v_readlane_b32 s99, v246, 2
	v_mov_b32_e32 v20, 0x3700
	s_nop 4
	global_load_dwordx4 v[24:27], v20, s[98:99] sc1
	global_load_dwordx4 v[28:31], v20, s[98:99] offset:16 sc1
	global_load_dwordx4 v[32:35], v20, s[98:99] offset:256 sc1
	global_load_dwordx4 v[40:43], v20, s[98:99] offset:272 sc1
	buffer_inv sc1
	s_waitcnt lgkmcnt(0)
	s_waitcnt vmcnt(0)
	v_add_u32_e32 v24, v24, v32
	v_xor_b32_e32 v24, 17, v24
	v_add_u32_e32 v25, v25, v33
	v_xor_b32_e32 v25, 17, v25
	v_add_u32_e32 v26, v26, v34
	v_xor_b32_e32 v26, 17, v26
	v_add_u32_e32 v27, v27, v35
	v_xor_b32_e32 v27, 17, v27
	v_add_u32_e32 v28, v28, v40
	v_xor_b32_e32 v28, 17, v28
	v_add_u32_e32 v29, v29, v41
	v_xor_b32_e32 v29, 17, v29
	v_add_u32_e32 v30, v30, v42
	v_xor_b32_e32 v30, 17, v30
	v_add_u32_e32 v31, v31, v43
	v_xor_b32_e32 v31, 17, v31
	v_or3_b32 v24, v24, v25, v26
	v_or3_b32 v27, v27, v28, v29
	v_or3_b32 v24, v24, v30, v31
	v_or_b32_e32 v24, v24, v27
	v_cmp_eq_u32_e32 vcc, 0, v24
	s_cbranch_vccnz .LBB0_876
	v_mbcnt_lo_u32_b32 v1, s8, 0
	v_mbcnt_hi_u32_b32 v1, s9, v1
	v_cmp_eq_u32_e32 vcc, 0, v1
	s_and_saveexec_b64 s[10:11], vcc
	s_cbranch_execz .LBB0_862
	s_bcnt1_i32_b64 s8, s[8:9]
	v_mov_b32_e32 v2, 0x283000
	v_mov_b32_e32 v3, s8
	global_atomic_add v2, v2, v3, s[76:77] offset:1024 sc0

	.amdhsa_kernel _Z6mk_fwd4Args
		.amdhsa_group_segment_fixed_size 0
		.amdhsa_private_segment_fixed_size 0
		.amdhsa_kernarg_size 400
		.amdhsa_user_sgpr_count 2
		.amdhsa_user_sgpr_dispatch_ptr 0
		.amdhsa_user_sgpr_queue_ptr 0
		.amdhsa_user_sgpr_kernarg_segment_ptr 1
		.amdhsa_user_sgpr_dispatch_id 0
		.amdhsa_user_sgpr_kernarg_preload_length 0
		.amdhsa_user_sgpr_kernarg_preload_offset 0
		.amdhsa_user_sgpr_private_segment_size 0
		.amdhsa_uses_dynamic_stack 0
		.amdhsa_enable_private_segment 0
		.amdhsa_system_sgpr_workgroup_id_x 1
		.amdhsa_system_sgpr_workgroup_id_y 0
		.amdhsa_system_sgpr_workgroup_id_z 0
		.amdhsa_system_sgpr_workgroup_info 0
		.amdhsa_system_vgpr_workitem_id 2
		.amdhsa_next_free_vgpr 247
		.amdhsa_next_free_sgpr 102
		.amdhsa_accum_offset 248
		.amdhsa_reserve_vcc 1
		.amdhsa_float_round_mode_32 0
		.amdhsa_float_round_mode_16_64 0
		.amdhsa_float_denorm_mode_32 3
		.amdhsa_float_denorm_mode_16_64 3
		.amdhsa_dx10_clamp 1
		.amdhsa_ieee_mode 1
		.amdhsa_fp16_overflow 0
		.amdhsa_tg_split 0
		.amdhsa_exception_fp_ieee_invalid_op 0
		.amdhsa_exception_fp_denorm_src 0
		.amdhsa_exception_fp_ieee_div_zero 0
		.amdhsa_exception_fp_ieee_overflow 0
		.amdhsa_exception_fp_ieee_underflow 0
		.amdhsa_exception_fp_ieee_inexact 0
		.amdhsa_exception_int_div_zero 0
	.end_amdhsa_kernel

amdhsa.kernels:
  - .agpr_count:     0
    .args:
      - .offset:         0
        .size:           144
        .value_kind:     by_value
      - .offset:         144
        .size:           4
        .value_kind:     hidden_block_count_x
      - .offset:         148
        .size:           4
        .value_kind:     hidden_block_count_y
      - .offset:         152
        .size:           4
        .value_kind:     hidden_block_count_z
      - .offset:         156
        .size:           2
        .value_kind:     hidden_group_size_x
      - .offset:         158
        .size:           2
        .value_kind:     hidden_group_size_y
      - .offset:         160
        .size:           2
        .value_kind:     hidden_group_size_z
      - .offset:         162
        .size:           2
        .value_kind:     hidden_remainder_x
      - .offset:         164
        .size:           2
        .value_kind:     hidden_remainder_y
      - .offset:         166
        .size:           2
        .value_kind:     hidden_remainder_z
      - .offset:         184
        .size:           8
        .value_kind:     hidden_global_offset_x
      - .offset:         192
        .size:           8
        .value_kind:     hidden_global_offset_y
      - .offset:         200
        .size:           8
        .value_kind:     hidden_global_offset_z
      - .offset:         208
        .size:           2
        .value_kind:     hidden_grid_dims
      - .offset:         232
        .size:           8
        .value_kind:     hidden_multigrid_sync_arg
      - .offset:         264
        .size:           4
        .value_kind:     hidden_dynamic_lds_size
    .group_segment_fixed_size: 0
    .kernarg_segment_align: 8
    .kernarg_segment_size: 400
    .language:       OpenCL C
    .language_version:
      - 2
      - 0
    .max_flat_workgroup_size: 512
    .name:           _Z6mk_fwd4Args
    .private_segment_fixed_size: 0
    .sgpr_count:     108
    .sgpr_spill_count: 58
    .symbol:         _Z6mk_fwd4Args.kd
    .uniform_work_group_size: 1
    .uses_dynamic_stack: false
    .vgpr_count:     247
    .vgpr_spill_count: 0
    .wavefront_size: 64
